# v48 + L2 touch-prefetch of the f32 residual rows in the first-layer EV-OUT epilogue (16 serialized load round trips now hit L2)
# baseline (speedup 1.0000x reference)
;     __device__ __forceinline__ void operator()(const f32x4 (&acc)[2][2][4][2], const Unit& u, int wr, int wc, int fr, int fq) const {
;     ...
;         for (int ai = 0; ai < 2; ++ai) {
;             u32x4 hv4[4][2];
;             if (!base32) {
; #pragma unroll
;                 for (int m = 0; m < 4; ++m)
; #pragma unroll
;                     for (int bj = 0; bj < 2; ++bj) hv4[m][bj] = *(const u32x4*)(hb + (size_t)(row0 + ai * HALF + m * 16) * 1024 + col0 + bj * HALF);
;             }
; #pragma unroll
;             for (int m = 0; m < 4; ++m) { const int row = row0 + ai * HALF + m * 16; const size_t off = (size_t)row * 1024 + col0; float s = 0.f;
; #pragma unroll
;                 for (int bj = 0; bj < 2; ++bj) { f32x4 b0, b1;
;                     if (base32) { b0 = *(const f32x4*)(base32 + off + bj * HALF); b1 = *(const f32x4*)(base32 + off + bj * HALF + 4); }
.LBB0_1083:
	v_lshlrev_b64 v[162:163], 10, v[188:189]
	v_lshl_add_u64 v[198:199], v[162:163], 0, v[190:191]
	s_and_b64 vcc, exec, s[8:9]
	v_lshl_add_u64 v[194:195], v[198:199], 2, s[18:19]
	s_cbranch_vccnz .LBB0_1155
	global_load_dword v68, v[194:195], off offset:512
	s_mov_b64 s[4:5], 0x10000
	v_lshl_add_u64 v[66:67], v[194:195], 0, s[4:5]
	global_load_dword v68, v[66:67], off
	global_load_dword v68, v[66:67], off offset:512
	s_mov_b64 s[4:5], 0x20000
	v_lshl_add_u64 v[66:67], v[194:195], 0, s[4:5]
	global_load_dword v68, v[66:67], off
	global_load_dword v68, v[66:67], off offset:512
	s_mov_b64 s[4:5], 0x30000
	v_lshl_add_u64 v[66:67], v[194:195], 0, s[4:5]
	global_load_dword v68, v[66:67], off
	global_load_dword v68, v[66:67], off offset:512
	s_mov_b64 s[4:5], 0x80000
	v_lshl_add_u64 v[66:67], v[194:195], 0, s[4:5]
	global_load_dword v68, v[66:67], off
	global_load_dword v68, v[66:67], off offset:512
	s_mov_b64 s[4:5], 0x90000
	v_lshl_add_u64 v[66:67], v[194:195], 0, s[4:5]
	global_load_dword v68, v[66:67], off
	global_load_dword v68, v[66:67], off offset:512
	s_mov_b64 s[4:5], 0xa0000
	v_lshl_add_u64 v[66:67], v[194:195], 0, s[4:5]
	global_load_dword v68, v[66:67], off
	global_load_dword v68, v[66:67], off offset:512
	s_mov_b64 s[4:5], 0xb0000
	v_lshl_add_u64 v[66:67], v[194:195], 0, s[4:5]
	global_load_dword v68, v[66:67], off
	global_load_dword v68, v[66:67], off offset:512
	global_load_dwordx4 v[166:169], v[194:195], off offset:16
	global_load_dwordx4 v[162:165], v[194:195], off
	s_cbranch_execnz .LBB0_1086
